# cvt_pk interleaved into the row-sum pk_add chains of both attention loops (hazard nops dropped)
# baseline (speedup 1.0000x reference)
; #define LAS __attribute__((address_space(3)))
; __device__ __forceinline__ void finishSM(f32x16& p0, f32x16& p1, float alpha, float& l_reg, bf16x8& pa0, bf16x8& pa1, bf16x8& pa2, bf16x8& pa3) {
; #pragma unroll
;     for (int r = 0; r < 16; ++r) p1[r] = __builtin_amdgcn_exp2f(p1[r]);
;     typedef float f32x2 __attribute__((ext_vector_type(2)));
;     f32x2 s2 = (f32x2){p0[0], p0[1]};
; #pragma unroll
;     for (int r = 2; r < 16; r += 2) s2 += (f32x2){p0[r], p0[r + 1]};
; #pragma unroll
;     for (int r = 0; r < 16; r += 2) s2 += (f32x2){p1[r], p1[r + 1]};
;     float ps = s2.x + s2.y;
;     { auto rr = __builtin_amdgcn_permlane32_swap(__float_as_uint(ps), __float_as_uint(ps), false, false);
;       ps = __uint_as_float(rr[0]) + __uint_as_float(rr[1]); }
;     l_reg = l_reg * alpha + ps;
;     ...
;     PK4(p0, 0, pa0); PK4(p0, 8, pa1); PK4(p1, 0, pa2); PK4(p1, 8, pa3);
;     ...
; }
; template <int MODE> __device__ __forceinline__ void qkt(f32x16& p0, f32x16& p1, const LAS unsigned char* Kt, const LAS unsigned char* Krt, const bf16x8* qr, int r32, int hi, int comp) {
;     p0 = f32x16{}; p1 = f32x16{};
;     constexpr int NDN = MODE ? 8 : 4;
; #pragma unroll
;     for (int d0 = 0; d0 < NDN; ++d0) { const int cb = ((MODE ? 0 : comp * 64) + d0 * 16 + hi * 8) * 2;
;         const bf16x8 b0 = *(const LAS bf16x8*)(Kt + KSWZ(r32, cb));
;         const bf16x8 b1 = *(const LAS bf16x8*)(Kt + KSWZ(32 + r32, cb));
;         p0 = __builtin_amdgcn_mfma_f32_32x32x16_bf16(b0, qr[d0], p0, 0, 0, 0);
;         p1 = __builtin_amdgcn_mfma_f32_32x32x16_bf16(b1, qr[d0], p1, 0, 0, 0); }
.LBB0_555:
	ds_read_b128 v[80:83], v172 offset:49152
	ds_read_b128 v[84:87], v172 offset:57344
	ds_read_b128 v[190:193], v174 offset:49152
	ds_read_b128 v[194:197], v174 offset:57344
	v_exp_f32_e32 v112, v112
	v_exp_f32_e32 v113, v113
	s_waitcnt lgkmcnt(0)
	v_mfma_f32_32x32x16_bf16 v[96:111], v[80:83], v[140:143], v[216:231]
	v_exp_f32_e32 v114, v114
	v_exp_f32_e32 v115, v115
	v_exp_f32_e32 v122, v122
	v_exp_f32_e32 v123, v123
	v_exp_f32_e32 v124, v124
	v_exp_f32_e32 v125, v125
	v_exp_f32_e32 v126, v126
	v_mfma_f32_32x32x16_bf16 v[80:95], v[84:87], v[140:143], v[216:231]
	v_exp_f32_e32 v127, v127
	v_mfma_f32_32x32x16_bf16 v[96:111], v[190:193], v[136:139], v[96:111]
	v_mfma_f32_32x32x16_bf16 v[80:95], v[194:197], v[136:139], v[80:95]
	ds_read_b128 v[190:193], v176 offset:49152
	ds_read_b128 v[194:197], v176 offset:57344
	s_waitcnt lgkmcnt(0)
	v_mfma_f32_32x32x16_bf16 v[96:111], v[190:193], v[132:135], v[96:111]
	v_mfma_f32_32x32x16_bf16 v[80:95], v[194:197], v[132:135], v[80:95]
	ds_read_b128 v[190:193], v178 offset:49152
	ds_read_b128 v[194:197], v178 offset:57344
	s_waitcnt lgkmcnt(0)
	v_mfma_f32_32x32x16_bf16 v[96:111], v[190:193], v[128:131], v[96:111]
	v_exp_f32_e32 v190, v116
	v_exp_f32_e32 v191, v117
	v_pk_add_f32 v[116:117], v[64:65], v[66:67]
	v_exp_f32_e32 v192, v118
	v_pk_add_f32 v[116:117], v[68:69], v[116:117]
	v_exp_f32_e32 v193, v119
	v_pk_add_f32 v[116:117], v[70:71], v[116:117]
	v_mfma_f32_32x32x16_bf16 v[80:95], v[194:197], v[128:131], v[80:95]
	v_add_f32_e64 v116, v72, v116
	v_add_f32_e64 v117, v73, v117
	v_exp_f32_e32 v194, v120
	v_pk_add_f32 v[116:117], v[74:75], v[116:117]
	v_exp_f32_e32 v195, v121
	v_pk_add_f32 v[116:117], v[76:77], v[116:117]
	v_cvt_pk_bf16_f32 v72, v72, v73
	v_pk_add_f32 v[116:117], v[78:79], v[116:117]
	v_cvt_pk_bf16_f32 v73, v74, v75
	v_pk_add_f32 v[116:117], v[112:113], v[116:117]
	v_cvt_pk_bf16_f32 v74, v76, v77
	v_pk_add_f32 v[116:117], v[114:115], v[116:117]
	v_cvt_pk_bf16_f32 v75, v78, v79
	v_pk_add_f32 v[116:117], v[190:191], v[116:117]
	v_cvt_pk_bf16_f32 v76, v112, v113
	v_pk_add_f32 v[116:117], v[192:193], v[116:117]
	v_cvt_pk_bf16_f32 v77, v114, v115
	v_pk_add_f32 v[116:117], v[194:195], v[116:117]
	v_cvt_pk_bf16_f32 v78, v190, v191
	v_pk_add_f32 v[116:117], v[122:123], v[116:117]
	v_cvt_pk_bf16_f32 v79, v192, v193
	v_pk_add_f32 v[116:117], v[124:125], v[116:117]
	v_cvt_pk_bf16_f32 v112, v194, v195
	v_pk_add_f32 v[116:117], v[126:127], v[116:117]
	v_cvt_pk_bf16_f32 v113, v122, v123
	v_pk_add_f32 v[120:121], v[116:117], v[116:117] op_sel:[0,1] op_sel_hi:[1,0]
	v_cvt_pk_bf16_f32 v114, v124, v125
	v_cvt_pk_bf16_f32 v115, v126, v127
	v_mov_b32_e32 v121, v120
	v_cvt_pk_bf16_f32 v116, v64, v65
	v_cvt_pk_bf16_f32 v117, v66, v67
	v_cvt_pk_bf16_f32 v118, v68, v69
	v_cvt_pk_bf16_f32 v119, v70, v71
	v_permlane32_swap_b32_e32 v120, v121
	s_and_b64 vcc, exec, s[4:5]
	s_cbranch_vccnz .LBB0_557
	s_waitcnt vmcnt(0) lgkmcnt(0)
	s_barrier

; #define LAS __attribute__((address_space(3)))
; __device__ __forceinline__ void finishSM(f32x16& p0, f32x16& p1, float alpha, float& l_reg, bf16x8& pa0, bf16x8& pa1, bf16x8& pa2, bf16x8& pa3) {
; #pragma unroll
;     for (int r = 0; r < 16; ++r) p1[r] = __builtin_amdgcn_exp2f(p1[r]);
;     typedef float f32x2 __attribute__((ext_vector_type(2)));
;     f32x2 s2 = (f32x2){p0[0], p0[1]};
; #pragma unroll
;     for (int r = 2; r < 16; r += 2) s2 += (f32x2){p0[r], p0[r + 1]};
; #pragma unroll
;     for (int r = 0; r < 16; r += 2) s2 += (f32x2){p1[r], p1[r + 1]};
;     float ps = s2.x + s2.y;
;     { auto rr = __builtin_amdgcn_permlane32_swap(__float_as_uint(ps), __float_as_uint(ps), false, false);
;       ps = __uint_as_float(rr[0]) + __uint_as_float(rr[1]); }
;     l_reg = l_reg * alpha + ps;
;     ...
;     PK4(p0, 0, pa0); PK4(p0, 8, pa1); PK4(p1, 0, pa2); PK4(p1, 8, pa3);
;     ...
; }
; template <int MODE> __device__ __forceinline__ void qkt(f32x16& p0, f32x16& p1, const LAS unsigned char* Kt, const LAS unsigned char* Krt, const bf16x8* qr, int r32, int hi, int comp) {
;     p0 = f32x16{}; p1 = f32x16{};
;     constexpr int NDN = MODE ? 8 : 4;
; #pragma unroll
;     for (int d0 = 0; d0 < NDN; ++d0) { const int cb = ((MODE ? 0 : comp * 64) + d0 * 16 + hi * 8) * 2;
;         const bf16x8 b0 = *(const LAS bf16x8*)(Kt + KSWZ(r32, cb));
;         const bf16x8 b1 = *(const LAS bf16x8*)(Kt + KSWZ(32 + r32, cb));
;         p0 = __builtin_amdgcn_mfma_f32_32x32x16_bf16(b0, qr[d0], p0, 0, 0, 0);
;         p1 = __builtin_amdgcn_mfma_f32_32x32x16_bf16(b1, qr[d0], p1, 0, 0, 0); }
;     if constexpr (MODE == 1) {
; #pragma unroll
;         for (int d0 = 0; d0 < 4; ++d0) { const int cb = (d0 * 16 + hi * 8) * 2;
;             const bf16x8 b0 = *(const LAS bf16x8*)(Krt + KRSWZ(r32, cb));
;             const bf16x8 b1 = *(const LAS bf16x8*)(Krt + KRSWZ(32 + r32, cb));
;             p0 = __builtin_amdgcn_mfma_f32_32x32x16_bf16(b0, qr[8 + d0], p0, 0, 0, 0);
;             p1 = __builtin_amdgcn_mfma_f32_32x32x16_bf16(b1, qr[8 + d0], p1, 0, 0, 0); }
;     }
; }
.LBB0_614:
	s_nop 0
	ds_read_b128 v[80:83], v205 offset:49152
	ds_read_b128 v[84:87], v205 offset:57344
	ds_read_b128 v[248:251], v207 offset:49152
	ds_read_b128 v[198:201], v207 offset:57344
	ds_read_b128 v[234:237], v209 offset:49152
	ds_read_b128 v[238:241], v209 offset:57344
	v_exp_f32_e32 v112, v112
	v_exp_f32_e32 v113, v113
	s_waitcnt lgkmcnt(4)
	v_mfma_f32_32x32x16_bf16 v[96:111], v[80:83], v[172:175], 0
	v_exp_f32_e32 v114, v114
	v_exp_f32_e32 v115, v115
	v_exp_f32_e32 v122, v122
	v_exp_f32_e32 v123, v123
	v_exp_f32_e32 v124, v124
	v_exp_f32_e32 v125, v125
	v_exp_f32_e32 v126, v126
	v_mfma_f32_32x32x16_bf16 v[80:95], v[84:87], v[172:175], 0
	v_exp_f32_e32 v127, v127
	s_waitcnt lgkmcnt(2)
	v_mfma_f32_32x32x16_bf16 v[96:111], v[248:251], v[168:171], v[96:111]
	v_mfma_f32_32x32x16_bf16 v[80:95], v[198:201], v[168:171], v[80:95]
	ds_read_b128 v[198:201], v211 offset:49152
	ds_read_b128 v[248:251], v211 offset:57344
	s_waitcnt lgkmcnt(2)
	v_mfma_f32_32x32x16_bf16 v[96:111], v[234:237], v[164:167], v[96:111]
	v_mfma_f32_32x32x16_bf16 v[80:95], v[238:241], v[164:167], v[80:95]
	ds_read_b128 v[234:237], v213 offset:49152
	ds_read_b128 v[238:241], v213 offset:57344
	s_waitcnt lgkmcnt(2)
	v_mfma_f32_32x32x16_bf16 v[96:111], v[198:201], v[160:163], v[96:111]
	v_mfma_f32_32x32x16_bf16 v[80:95], v[248:251], v[160:163], v[80:95]
	ds_read_b128 v[198:201], v215 offset:49152
	ds_read_b128 v[248:251], v215 offset:57344
	s_waitcnt lgkmcnt(2)
	v_mfma_f32_32x32x16_bf16 v[96:111], v[234:237], v[156:159], v[96:111]
	v_mfma_f32_32x32x16_bf16 v[80:95], v[238:241], v[156:159], v[80:95]
	ds_read_b128 v[234:237], v217 offset:49152
	ds_read_b128 v[238:241], v217 offset:57344
	s_waitcnt lgkmcnt(2)
	v_mfma_f32_32x32x16_bf16 v[96:111], v[198:201], v[152:155], v[96:111]
	v_mfma_f32_32x32x16_bf16 v[80:95], v[248:251], v[152:155], v[80:95]
	ds_read_b128 v[198:201], v219 offset:49152
	ds_read_b128 v[248:251], v219 offset:57344
	s_waitcnt lgkmcnt(2)
	v_mfma_f32_32x32x16_bf16 v[96:111], v[234:237], v[148:151], v[96:111]
	v_mfma_f32_32x32x16_bf16 v[80:95], v[238:241], v[148:151], v[80:95]
	ds_read_b128 v[234:237], v221
	ds_read_b128 v[238:241], v221 offset:4096
	s_waitcnt lgkmcnt(2)
	v_mfma_f32_32x32x16_bf16 v[96:111], v[198:201], v[144:147], v[96:111]
	v_mfma_f32_32x32x16_bf16 v[80:95], v[248:251], v[144:147], v[80:95]
	ds_read_b128 v[198:201], v223
	ds_read_b128 v[248:251], v223 offset:4096
	s_waitcnt lgkmcnt(2)
	v_mfma_f32_32x32x16_bf16 v[96:111], v[234:237], v[140:143], v[96:111]
	v_mfma_f32_32x32x16_bf16 v[80:95], v[238:241], v[140:143], v[80:95]
	ds_read_b128 v[234:237], v225
	ds_read_b128 v[238:241], v225 offset:4096
	s_waitcnt lgkmcnt(2)
	v_mfma_f32_32x32x16_bf16 v[96:111], v[198:201], v[136:139], v[96:111]
	v_mfma_f32_32x32x16_bf16 v[80:95], v[248:251], v[136:139], v[80:95]
	ds_read_b128 v[198:201], v227
	ds_read_b128 v[248:251], v227 offset:4096
	s_waitcnt lgkmcnt(2)
	v_mfma_f32_32x32x16_bf16 v[96:111], v[234:237], v[132:135], v[96:111]
	v_mfma_f32_32x32x16_bf16 v[80:95], v[238:241], v[132:135], v[80:95]
	s_waitcnt lgkmcnt(0)
	v_mfma_f32_32x32x16_bf16 v[96:111], v[198:201], v[128:131], v[96:111]
	v_exp_f32_e32 v198, v116
	v_exp_f32_e32 v199, v117
	v_pk_add_f32 v[116:117], v[64:65], v[66:67]
	v_exp_f32_e32 v200, v118
	v_pk_add_f32 v[116:117], v[68:69], v[116:117]
	v_exp_f32_e32 v201, v119
	v_pk_add_f32 v[116:117], v[70:71], v[116:117]
	v_mfma_f32_32x32x16_bf16 v[80:95], v[248:251], v[128:131], v[80:95]
	v_add_f32_e64 v116, v72, v116
	v_add_f32_e64 v117, v73, v117
	v_exp_f32_e32 v248, v120
	v_pk_add_f32 v[116:117], v[74:75], v[116:117]
	v_exp_f32_e32 v249, v121
	v_pk_add_f32 v[116:117], v[76:77], v[116:117]
	v_cvt_pk_bf16_f32 v72, v72, v73
	v_pk_add_f32 v[116:117], v[78:79], v[116:117]
	v_cvt_pk_bf16_f32 v73, v74, v75
	v_pk_add_f32 v[116:117], v[112:113], v[116:117]
	v_cvt_pk_bf16_f32 v74, v76, v77
	v_pk_add_f32 v[116:117], v[114:115], v[116:117]
	v_cvt_pk_bf16_f32 v75, v78, v79
	v_pk_add_f32 v[116:117], v[198:199], v[116:117]
	v_cvt_pk_bf16_f32 v76, v112, v113
	v_pk_add_f32 v[116:117], v[200:201], v[116:117]
	v_cvt_pk_bf16_f32 v77, v114, v115
	v_pk_add_f32 v[116:117], v[248:249], v[116:117]
	v_cvt_pk_bf16_f32 v78, v198, v199
	v_pk_add_f32 v[116:117], v[122:123], v[116:117]
	v_cvt_pk_bf16_f32 v79, v200, v201
	v_pk_add_f32 v[116:117], v[124:125], v[116:117]
	v_cvt_pk_bf16_f32 v112, v248, v249
	v_pk_add_f32 v[116:117], v[126:127], v[116:117]
	v_cvt_pk_bf16_f32 v113, v122, v123
	v_pk_add_f32 v[120:121], v[116:117], v[116:117] op_sel:[0,1] op_sel_hi:[1,0]
	v_cvt_pk_bf16_f32 v114, v124, v125
	v_cvt_pk_bf16_f32 v115, v126, v127
	v_mov_b32_e32 v121, v120
	v_cvt_pk_bf16_f32 v116, v64, v65
	v_cvt_pk_bf16_f32 v117, v66, v67
	v_cvt_pk_bf16_f32 v118, v68, v69
	v_cvt_pk_bf16_f32 v119, v70, v71
	v_permlane32_swap_b32_e32 v120, v121
	s_and_b64 vcc, exec, s[4:5]
	s_cbranch_vccnz .LBB0_616
	s_waitcnt vmcnt(0) lgkmcnt(0)
	s_barrier
